# packed-to-scalar fp32 split: every v_pk_fma/mul/add_f32 in the selected-branch loop replaced by two single f32 ops (bit-identical)
# speedup vs baseline: 1.0019x; 1.0019x over previous
.LBB0_419:
	s_cmp_eq_u32 s13, s12
	s_cbranch_scc1 .LBB0_418
	s_or_b32 s6, s13, s5
	s_ff1_i32_b64 s18, s[8:9]
	s_lshl_b32 s6, s6, 14
	s_and_b32 s6, s6, 0xc000
	s_lshl_b32 s14, s18, 6
	s_add_i32 s13, s6, 0
	s_or_b32 s16, s14, 63
	s_mov_b64 s[6:7], -1
	s_cmp_ge_i32 s16, s1
	v_lshrrev_b64 v[162:163], s18, v[38:39]
	v_lshrrev_b64 v[164:165], s18, v[40:41]
	s_cbranch_scc0 .LBB0_439
	s_cmp_le_i32 s16, s2
	s_cselect_b64 s[6:7], -1, 0
	s_cmp_gt_i32 s14, s4
	v_and_b32_e32 v0, 1, v164
	s_cselect_b64 s[18:19], -1, 0
	v_cmp_eq_u32_e64 s[42:43], 1, v0
	v_and_b32_e32 v0, 1, v162
	s_and_b64 s[18:19], s[6:7], s[18:19]
	v_cmp_eq_u32_e64 s[44:45], 1, v0
	s_andn2_b64 vcc, exec, s[18:19]
	s_or_b64 s[18:19], s[44:45], s[42:43]
	s_mov_b64 s[6:7], -1
	v_cndmask_b32_e64 v139, 0, 1, s[18:19]
	s_cbranch_vccz .LBB0_430
	v_cmp_ne_u32_e32 vcc, 0, v139
	s_cbranch_vccz .Lsel_fast
	v_add_u32_e32 v54, s13, v196
	v_cmp_ne_u32_e32 vcc, 0, v0
	v_sub_u32_e32 v0, s14, v140
	v_add_u32_e32 v62, v54, v194
	v_add_u32_e32 v89, v54, v195
	v_lshl_add_u32 v0, v0, 2, v216
	s_cbranch_vccz .Lp0_skip0
	v_add_u32_e32 v63, 0xffc, v0
	ds_read_b128 v[54:57], v62 offset:16384
	ds_read_b128 v[58:61], v62 offset:18432
	ds_read_b128 v[64:67], v62 offset:20480
	ds_read_b128 v[68:71], v89 offset:16384
	ds_read_b128 v[72:75], v62 offset:22528
	ds_read2_b32 v[90:91], v63 offset1:1
	ds_read2_b32 v[92:93], v63 offset0:2 offset1:3
	ds_read2_b32 v[94:95], v63 offset0:16 offset1:17
	ds_read2_b32 v[96:97], v63 offset0:18 offset1:19
	ds_read2_b32 v[98:99], v63 offset0:32 offset1:33
	ds_read2_b32 v[100:101], v63 offset0:34 offset1:35
	ds_read2_b32 v[154:155], v63 offset0:48 offset1:49
	ds_read2_b32 v[156:157], v63 offset0:50 offset1:51
	s_waitcnt lgkmcnt(8)
	s_setprio 1
	v_mfma_f32_16x16x32_bf16 v[54:57], v[54:57], v[2:5], 0
	v_mfma_f32_16x16x32_bf16 v[58:61], v[58:61], v[2:5], 0
	v_mfma_f32_16x16x32_bf16 v[54:57], v[68:71], v[6:9], v[54:57]
	ds_read_b128 v[68:71], v89 offset:18432
	ds_read_b128 v[76:79], v89 offset:20480
	v_mfma_f32_16x16x32_bf16 v[64:67], v[64:67], v[2:5], 0
	v_mfma_f32_16x16x32_bf16 v[84:87], v[72:75], v[2:5], 0
	s_waitcnt lgkmcnt(0)
	v_mfma_f32_16x16x32_bf16 v[58:61], v[68:71], v[6:9], v[58:61]
	ds_read_b128 v[68:71], v89 offset:22528
	v_mfma_f32_16x16x32_bf16 v[64:67], v[76:79], v[6:9], v[64:67]
	s_waitcnt lgkmcnt(0)
	v_mfma_f32_16x16x32_bf16 v[84:87], v[68:71], v[6:9], v[84:87]
	s_setprio 0
	v_fma_f32 v54, v54, s36, v90
	v_fma_f32 v55, v55, s36, v91
	v_fma_f32 v56, v56, s36, v92
	v_fma_f32 v57, v57, s36, v93
	s_nop 1
	v_fma_f32 v58, v58, s36, v94
	v_fma_f32 v59, v59, s36, v95
	v_fma_f32 v60, v60, s36, v96
	v_fma_f32 v61, v61, s36, v97
	v_fma_f32 v64, v64, s36, v98
	v_fma_f32 v65, v65, s36, v99
	v_fma_f32 v66, v66, s36, v100
	v_fma_f32 v67, v67, s36, v101
	v_fma_f32 v84, v84, s36, v154
	v_fma_f32 v85, v85, s36, v155
	v_fma_f32 v86, v86, s36, v156
	v_fma_f32 v87, v87, s36, v157
	v_or_b32_e32 v83, s14, v197
	v_sub_u32_e32 v88, v140, v83
	v_cmp_le_i32_e64 s[6:7], 0, v88
	v_cmp_le_i32_e64 s[18:19], 1, v88
	v_cmp_le_i32_e64 s[98:99], 2, v88
	v_cmp_le_i32_e64 s[100:101], 3, v88
	v_cndmask_b32_e64 v54, v148, v54, s[6:7]
	v_cndmask_b32_e64 v55, v148, v55, s[18:19]
	v_cndmask_b32_e64 v56, v148, v56, s[98:99]
	v_cndmask_b32_e64 v57, v148, v57, s[100:101]
	v_cmp_le_i32_e64 s[6:7], 16, v88
	v_cmp_le_i32_e64 s[18:19], 17, v88
	v_cmp_le_i32_e64 s[98:99], 18, v88
	v_cmp_le_i32_e64 s[100:101], 19, v88
	v_cndmask_b32_e64 v58, v148, v58, s[6:7]
	v_cndmask_b32_e64 v59, v148, v59, s[18:19]
	v_cndmask_b32_e64 v60, v148, v60, s[98:99]
	v_cndmask_b32_e64 v61, v148, v61, s[100:101]
	v_cmp_le_i32_e64 s[6:7], 32, v88
	v_cmp_le_i32_e64 s[18:19], 33, v88
	v_cmp_le_i32_e64 s[98:99], 34, v88
	v_cmp_le_i32_e64 s[100:101], 35, v88
	v_cndmask_b32_e64 v64, v148, v64, s[6:7]
	v_cndmask_b32_e64 v65, v148, v65, s[18:19]
	v_cndmask_b32_e64 v66, v148, v66, s[98:99]
	v_cndmask_b32_e64 v67, v148, v67, s[100:101]
	v_cmp_le_i32_e64 s[6:7], 48, v88
	v_cmp_le_i32_e64 s[18:19], 49, v88
	v_cmp_le_i32_e64 s[98:99], 50, v88
	v_cmp_le_i32_e64 s[100:101], 51, v88
	v_cndmask_b32_e64 v84, v148, v84, s[6:7]
	v_cndmask_b32_e64 v85, v148, v85, s[18:19]
	v_cndmask_b32_e64 v86, v148, v86, s[98:99]
	v_cndmask_b32_e64 v87, v148, v87, s[100:101]
	v_max3_f32 v63, v54, v55, v56
	v_max3_f32 v63, v63, v57, v58
	v_max3_f32 v63, v63, v59, v60
	v_max3_f32 v63, v63, v61, v64
	v_max3_f32 v63, v63, v65, v66
	v_max3_f32 v63, v63, v67, v84
	v_max3_f32 v63, v63, v85, v86
	v_max3_f32 v63, v63, v87, s29
	v_mov_b32_e32 v68, v63
	s_nop 1
	v_permlane16_swap_b32_e32 v63, v68
	v_max_f32_e32 v63, v63, v68
	v_mov_b32_e32 v68, v63
	s_nop 1
	v_permlane32_swap_b32_e32 v63, v68
	v_max_f32_e32 v63, v63, v68
	v_cndmask_b32_e64 v63, v148, v63, s[44:45]
	v_max_f32_e32 v68, v160, v63
	v_sub_f32_e32 v69, v160, v68
	v_exp_f32_e32 v70, v69
	v_cndmask_b32_e64 v82, v209, v68, s[44:45]
	v_mov_b32_e32 v160, v68
	v_mul_f32_e32 v36, v36, v70
	v_mul_f32_e32 v37, v37, v70
	v_mul_f32_e32 v34, v34, v70
	v_mul_f32_e32 v35, v35, v70
	v_mul_f32_e32 v48, v48, v70
	v_mul_f32_e32 v49, v49, v70
	v_mul_f32_e32 v46, v46, v70
	v_mul_f32_e32 v47, v47, v70
	v_mul_f32_e32 v44, v44, v70
	v_mul_f32_e32 v45, v45, v70
	v_mul_f32_e32 v42, v42, v70
	v_mul_f32_e32 v43, v43, v70
	v_mul_f32_e32 v52, v52, v70
	v_mul_f32_e32 v53, v53, v70
	v_mul_f32_e32 v50, v50, v70
	v_mul_f32_e32 v51, v51, v70
	v_sub_f32_e32 v54, v54, v82
	v_sub_f32_e32 v55, v55, v82
	v_sub_f32_e32 v56, v56, v82
	v_sub_f32_e32 v57, v57, v82
	v_sub_f32_e32 v58, v58, v82
	v_sub_f32_e32 v59, v59, v82
	v_sub_f32_e32 v60, v60, v82
	v_sub_f32_e32 v61, v61, v82
	v_sub_f32_e32 v64, v64, v82
	v_sub_f32_e32 v65, v65, v82
	v_sub_f32_e32 v66, v66, v82
	v_sub_f32_e32 v67, v67, v82
	v_sub_f32_e32 v84, v84, v82
	v_sub_f32_e32 v85, v85, v82
	v_sub_f32_e32 v86, v86, v82
	v_sub_f32_e32 v87, v87, v82
	v_exp_f32_e32 v54, v54
	v_exp_f32_e32 v55, v55
	v_exp_f32_e32 v56, v56
	v_exp_f32_e32 v57, v57
	v_exp_f32_e32 v58, v58
	v_exp_f32_e32 v59, v59
	v_exp_f32_e32 v60, v60
	v_exp_f32_e32 v61, v61
	v_exp_f32_e32 v64, v64
	v_exp_f32_e32 v65, v65
	v_exp_f32_e32 v66, v66
	v_exp_f32_e32 v67, v67
	v_exp_f32_e32 v84, v84
	v_exp_f32_e32 v85, v85
	v_exp_f32_e32 v86, v86
	v_exp_f32_e32 v87, v87
	s_nop 0
	v_add_f32_e32 v72, v54, v56
	v_add_f32_e32 v73, v55, v57
	v_add_f32_e32 v74, v58, v60
	v_add_f32_e32 v75, v59, v61
	v_add_f32_e32 v76, v64, v66
	v_add_f32_e32 v77, v65, v67
	v_add_f32_e32 v78, v84, v86
	v_add_f32_e32 v79, v85, v87
	v_add_f32_e32 v72, v72, v74
	v_add_f32_e32 v73, v73, v75
	v_add_f32_e32 v76, v76, v78
	v_add_f32_e32 v77, v77, v79
	s_nop 0
	v_add_f32_e32 v72, v72, v76
	v_add_f32_e32 v73, v73, v77
	s_nop 0
	v_add_f32_e32 v72, v72, v73
	v_fma_f32 v144, v144, v70, v72
	v_cvt_pk_bf16_f32 v61, v60, v61
	v_cvt_pk_bf16_f32 v60, v58, v59
	v_cvt_pk_bf16_f32 v59, v56, v57
	v_cvt_pk_bf16_f32 v58, v54, v55
	v_cvt_pk_bf16_f32 v54, v64, v65
	v_cvt_pk_bf16_f32 v55, v66, v67
	v_cvt_pk_bf16_f32 v56, v84, v85
	v_cvt_pk_bf16_f32 v57, v86, v87
	v_cndmask_b32_e64 v63, 0, 1, s[42:43]
	v_cmp_ne_u32_e32 vcc, 0, v63
	s_cbranch_vccz .LBB0_445
.Lp0_cb1:
	v_add_u32_e32 v88, 0xfec, v0
	ds_read_b128 v[64:67], v62 offset:16384
	ds_read_b128 v[68:71], v62 offset:18432
	ds_read_b128 v[72:75], v89 offset:16384
	ds_read_b128 v[76:79], v89 offset:18432
	ds_read2_b32 v[90:91], v88 offset1:1
	ds_read2_b32 v[92:93], v88 offset0:2 offset1:3
	ds_read2_b32 v[94:95], v88 offset0:16 offset1:17
	ds_read2_b32 v[96:97], v88 offset0:18 offset1:19
	ds_read2_b32 v[98:99], v88 offset0:32 offset1:33
	ds_read2_b32 v[100:101], v88 offset0:34 offset1:35
	ds_read2_b32 v[154:155], v88 offset0:48 offset1:49
	ds_read2_b32 v[156:157], v88 offset0:50 offset1:51
	s_waitcnt lgkmcnt(8)
	s_setprio 1
	v_mfma_f32_16x16x32_bf16 v[64:67], v[64:67], v[10:13], 0
	v_mfma_f32_16x16x32_bf16 v[68:71], v[68:71], v[10:13], 0
	v_mfma_f32_16x16x32_bf16 v[64:67], v[72:75], v[14:17], v[64:67]
	ds_read_b128 v[72:75], v62 offset:20480
	v_mfma_f32_16x16x32_bf16 v[68:71], v[76:79], v[14:17], v[68:71]
	ds_read_b128 v[76:79], v89 offset:20480
	ds_read_b128 v[80:83], v62 offset:22528
	ds_read_b128 v[84:87], v89 offset:22528
	s_waitcnt lgkmcnt(0)
	v_mfma_f32_16x16x32_bf16 v[72:75], v[72:75], v[10:13], 0
	v_mfma_f32_16x16x32_bf16 v[80:83], v[80:83], v[10:13], 0
	v_mfma_f32_16x16x32_bf16 v[72:75], v[76:79], v[14:17], v[72:75]
	v_mfma_f32_16x16x32_bf16 v[80:83], v[84:87], v[14:17], v[80:83]
	s_setprio 0
	v_fma_f32 v64, v64, s36, v90
	v_fma_f32 v65, v65, s36, v91
	v_fma_f32 v66, v66, s36, v92
	v_fma_f32 v67, v67, s36, v93
	v_fma_f32 v68, v68, s36, v94
	v_fma_f32 v69, v69, s36, v95
	v_fma_f32 v70, v70, s36, v96
	v_fma_f32 v71, v71, s36, v97
	s_nop 3
	v_fma_f32 v72, v72, s36, v98
	v_fma_f32 v73, v73, s36, v99
	v_fma_f32 v74, v74, s36, v100
	v_fma_f32 v75, v75, s36, v101
	v_fma_f32 v80, v80, s36, v154
	v_fma_f32 v81, v81, s36, v155
	v_fma_f32 v82, v82, s36, v156
	v_fma_f32 v83, v83, s36, v157
	v_or_b32_e32 v79, s14, v197
	v_sub_u32_e32 v88, v142, v79
	v_cmp_le_i32_e64 s[6:7], 0, v88
	v_cmp_le_i32_e64 s[18:19], 1, v88
	v_cmp_le_i32_e64 s[98:99], 2, v88
	v_cmp_le_i32_e64 s[100:101], 3, v88
	v_cndmask_b32_e64 v64, v148, v64, s[6:7]
	v_cndmask_b32_e64 v65, v148, v65, s[18:19]
	v_cndmask_b32_e64 v66, v148, v66, s[98:99]
	v_cndmask_b32_e64 v67, v148, v67, s[100:101]
	v_cmp_le_i32_e64 s[6:7], 16, v88
	v_cmp_le_i32_e64 s[18:19], 17, v88
	v_cmp_le_i32_e64 s[98:99], 18, v88
	v_cmp_le_i32_e64 s[100:101], 19, v88
	v_cndmask_b32_e64 v68, v148, v68, s[6:7]
	v_cndmask_b32_e64 v69, v148, v69, s[18:19]
	v_cndmask_b32_e64 v70, v148, v70, s[98:99]
	v_cndmask_b32_e64 v71, v148, v71, s[100:101]
	v_cmp_le_i32_e64 s[6:7], 32, v88
	v_cmp_le_i32_e64 s[18:19], 33, v88
	v_cmp_le_i32_e64 s[98:99], 34, v88
	v_cmp_le_i32_e64 s[100:101], 35, v88
	v_cndmask_b32_e64 v72, v148, v72, s[6:7]
	v_cndmask_b32_e64 v73, v148, v73, s[18:19]
	v_cndmask_b32_e64 v74, v148, v74, s[98:99]
	v_cndmask_b32_e64 v75, v148, v75, s[100:101]
	v_cmp_le_i32_e64 s[6:7], 48, v88
	v_cmp_le_i32_e64 s[18:19], 49, v88
	v_cmp_le_i32_e64 s[98:99], 50, v88
	v_cmp_le_i32_e64 s[100:101], 51, v88
	v_cndmask_b32_e64 v80, v148, v80, s[6:7]
	v_cndmask_b32_e64 v81, v148, v81, s[18:19]
	v_cndmask_b32_e64 v82, v148, v82, s[98:99]
	v_cndmask_b32_e64 v83, v148, v83, s[100:101]
	v_max3_f32 v76, v64, v65, v66
	v_max3_f32 v76, v76, v67, v68
	v_max3_f32 v76, v76, v69, v70
	v_max3_f32 v76, v76, v71, v72
	v_max3_f32 v76, v76, v73, v74
	v_max3_f32 v76, v76, v75, v80
	v_max3_f32 v76, v76, v81, v82
	v_max3_f32 v76, v76, v83, s29
	v_mov_b32_e32 v77, v76
	s_nop 1
	v_permlane16_swap_b32_e32 v76, v77
	v_max_f32_e32 v76, v76, v77
	v_mov_b32_e32 v77, v76
	s_nop 1
	v_permlane32_swap_b32_e32 v76, v77
	v_max_f32_e32 v76, v76, v77
	v_cndmask_b32_e64 v76, v148, v76, s[42:43]
	v_max_f32_e32 v77, v161, v76
	v_sub_f32_e32 v0, v161, v77
	v_exp_f32_e32 v0, v0
	v_cndmask_b32_e64 v78, v209, v77, s[42:43]
	v_mov_b32_e32 v161, v77
	v_mul_f32_e32 v32, v32, v0
	v_mul_f32_e32 v33, v33, v0
	v_mul_f32_e32 v30, v30, v0
	v_mul_f32_e32 v31, v31, v0
	v_mul_f32_e32 v28, v28, v0
	v_mul_f32_e32 v29, v29, v0
	v_mul_f32_e32 v26, v26, v0
	v_mul_f32_e32 v27, v27, v0
	v_mul_f32_e32 v24, v24, v0
	v_mul_f32_e32 v25, v25, v0
	v_mul_f32_e32 v22, v22, v0
	v_mul_f32_e32 v23, v23, v0
	v_mul_f32_e32 v20, v20, v0
	v_mul_f32_e32 v21, v21, v0
	v_mul_f32_e32 v18, v18, v0
	v_mul_f32_e32 v19, v19, v0
	v_sub_f32_e32 v64, v64, v78
	v_sub_f32_e32 v65, v65, v78
	v_sub_f32_e32 v66, v66, v78
	v_sub_f32_e32 v67, v67, v78
	v_sub_f32_e32 v68, v68, v78
	v_sub_f32_e32 v69, v69, v78
	v_sub_f32_e32 v70, v70, v78
	v_sub_f32_e32 v71, v71, v78
	v_sub_f32_e32 v72, v72, v78
	v_sub_f32_e32 v73, v73, v78
	v_sub_f32_e32 v74, v74, v78
	v_sub_f32_e32 v75, v75, v78
	v_sub_f32_e32 v80, v80, v78
	v_sub_f32_e32 v81, v81, v78
	v_sub_f32_e32 v82, v82, v78
	v_sub_f32_e32 v83, v83, v78
	v_exp_f32_e32 v64, v64
	v_exp_f32_e32 v65, v65
	v_exp_f32_e32 v66, v66
	v_exp_f32_e32 v67, v67
	v_exp_f32_e32 v68, v68
	v_exp_f32_e32 v69, v69
	v_exp_f32_e32 v70, v70
	v_exp_f32_e32 v71, v71
	v_exp_f32_e32 v72, v72
	v_exp_f32_e32 v73, v73
	v_exp_f32_e32 v74, v74
	v_exp_f32_e32 v75, v75
	v_exp_f32_e32 v80, v80
	v_exp_f32_e32 v81, v81
	v_exp_f32_e32 v82, v82
	v_exp_f32_e32 v83, v83
	s_nop 0
	v_add_f32_e32 v84, v64, v66
	v_add_f32_e32 v85, v65, v67
	v_add_f32_e32 v86, v68, v70
	v_add_f32_e32 v87, v69, v71
	v_add_f32_e32 v76, v72, v74
	v_add_f32_e32 v77, v73, v75
	v_add_f32_e32 v78, v80, v82
	v_add_f32_e32 v79, v81, v83
	v_add_f32_e32 v84, v84, v86
	v_add_f32_e32 v85, v85, v87
	v_add_f32_e32 v76, v76, v78
	v_add_f32_e32 v77, v77, v79
	s_nop 0
	v_add_f32_e32 v84, v84, v76
	v_add_f32_e32 v85, v85, v77
	s_nop 0
	v_add_f32_e32 v84, v84, v85
	v_fma_f32 v145, v145, v0, v84
	v_cvt_pk_bf16_f32 v67, v66, v67
	v_cvt_pk_bf16_f32 v66, v64, v65
	v_cvt_pk_bf16_f32 v68, v68, v69
	v_cvt_pk_bf16_f32 v69, v70, v71
	v_cvt_pk_bf16_f32 v62, v72, v73
	v_cvt_pk_bf16_f32 v63, v74, v75
	v_cvt_pk_bf16_f32 v64, v80, v81
	v_cvt_pk_bf16_f32 v65, v82, v83
	s_branch .LBB0_446

.LBB0_430:
	s_andn2_b64 vcc, exec, s[6:7]
	s_cbranch_vccnz .LBB0_438
	v_cmp_ne_u32_e32 vcc, 0, v139
	s_cbranch_vccz .Lsel_fast
	v_add_u32_e32 v54, s13, v196
	v_sub_u32_e32 v0, s14, v140
	v_add_u32_e32 v62, v54, v194
	v_add_u32_e32 v89, v54, v195
	v_lshl_add_u32 v0, v0, 2, v216
	s_cmp_lg_u64 s[44:45], 0
	s_movk_i32 s98, 0xfec
	s_cselect_b32 s98, 0xffc, s98
	v_add_u32_e32 v230, s98, v0
	v_add_u32_e32 v231, 0xfec, v0
	ds_read_b128 v[64:67], v62 offset:16384
	ds_read_b128 v[54:57], v89 offset:16384
	ds_read_b128 v[68:71], v62 offset:18432
	ds_read_b128 v[58:61], v89 offset:18432
	ds_read_b128 v[72:75], v62 offset:20480
	ds_read_b128 v[76:79], v89 offset:20480
	ds_read_b128 v[80:83], v62 offset:22528
	ds_read_b128 v[84:87], v89 offset:22528
	ds_read2_b32 v[90:91], v230 offset1:1
	ds_read2_b32 v[92:93], v230 offset0:2 offset1:3
	ds_read2_b32 v[94:95], v230 offset0:16 offset1:17
	ds_read2_b32 v[96:97], v230 offset0:18 offset1:19
	s_waitcnt lgkmcnt(4)
	ds_read2_b32 v[98:99], v230 offset0:32 offset1:33
	ds_read2_b32 v[100:101], v230 offset0:34 offset1:35
	ds_read2_b32 v[154:155], v230 offset0:48 offset1:49
	ds_read2_b32 v[156:157], v230 offset0:50 offset1:51
	s_cbranch_scc0 .Lp1v_m1
	s_cmp_lg_u64 s[42:43], 0
	s_cbranch_scc0 .Lp1v_only0
	s_setprio 1
	v_mfma_f32_16x16x32_bf16 v[170:173], v[64:67], v[2:5], 0
	v_mfma_f32_16x16x32_bf16 v[174:177], v[68:71], v[2:5], 0
	v_mfma_f32_16x16x32_bf16 v[170:173], v[54:57], v[6:9], v[170:173]
	v_mfma_f32_16x16x32_bf16 v[178:181], v[72:75], v[2:5], 0
	v_mfma_f32_16x16x32_bf16 v[174:177], v[58:61], v[6:9], v[174:177]
	v_mfma_f32_16x16x32_bf16 v[182:185], v[80:83], v[2:5], 0
	v_mfma_f32_16x16x32_bf16 v[178:181], v[76:79], v[6:9], v[178:181]
	v_mfma_f32_16x16x32_bf16 v[182:185], v[84:87], v[6:9], v[182:185]
	v_mfma_f32_16x16x32_bf16 v[64:67], v[64:67], v[10:13], 0
	v_mfma_f32_16x16x32_bf16 v[68:71], v[68:71], v[10:13], 0
	v_mfma_f32_16x16x32_bf16 v[64:67], v[54:57], v[14:17], v[64:67]
	v_mfma_f32_16x16x32_bf16 v[72:75], v[72:75], v[10:13], 0
	v_mfma_f32_16x16x32_bf16 v[68:71], v[58:61], v[14:17], v[68:71]
	v_mfma_f32_16x16x32_bf16 v[80:83], v[80:83], v[10:13], 0
	v_mfma_f32_16x16x32_bf16 v[72:75], v[76:79], v[14:17], v[72:75]
	v_mfma_f32_16x16x32_bf16 v[80:83], v[84:87], v[14:17], v[80:83]
	s_setprio 0
	s_waitcnt lgkmcnt(0)
	v_fma_f32 v170, v170, s36, v90
	v_fma_f32 v171, v171, s36, v91
	v_fma_f32 v172, v172, s36, v92
	v_fma_f32 v173, v173, s36, v93
	v_fma_f32 v174, v174, s36, v94
	v_fma_f32 v175, v175, s36, v95
	v_fma_f32 v176, v176, s36, v96
	v_fma_f32 v177, v177, s36, v97
	v_fma_f32 v178, v178, s36, v98
	v_fma_f32 v179, v179, s36, v99
	v_fma_f32 v180, v180, s36, v100
	v_fma_f32 v181, v181, s36, v101
	v_fma_f32 v182, v182, s36, v154
	v_fma_f32 v183, v183, s36, v155
	v_fma_f32 v184, v184, s36, v156
	v_fma_f32 v185, v185, s36, v157
	ds_read2_b32 v[90:91], v231 offset1:1
	ds_read2_b32 v[92:93], v231 offset0:2 offset1:3
	ds_read2_b32 v[94:95], v231 offset0:16 offset1:17
	ds_read2_b32 v[96:97], v231 offset0:18 offset1:19
	ds_read2_b32 v[98:99], v231 offset0:32 offset1:33
	ds_read2_b32 v[100:101], v231 offset0:34 offset1:35
	ds_read2_b32 v[154:155], v231 offset0:48 offset1:49
	ds_read2_b32 v[156:157], v231 offset0:50 offset1:51
	v_max3_f32 v186, v170, v171, v172
	v_max3_f32 v186, v186, v173, v174
	v_max3_f32 v186, v186, v175, v176
	v_max3_f32 v186, v186, v177, v178
	v_max3_f32 v186, v186, v179, v180
	v_max3_f32 v186, v186, v181, v182
	v_max3_f32 v186, v186, v183, v184
	v_max3_f32 v186, v186, v185, s29
	v_mov_b32_e32 v187, v186
	s_nop 1
	v_permlane16_swap_b32_e32 v186, v187
	v_max_f32_e32 v186, v186, v187
	v_mov_b32_e32 v187, v186
	s_nop 1
	v_permlane32_swap_b32_e32 v186, v187
	v_max_f32_e32 v186, v186, v187
	v_cndmask_b32_e64 v186, v148, v186, s[44:45]
	v_max_f32_e32 v187, v160, v186
	s_waitcnt lgkmcnt(0)
	v_fma_f32 v64, v64, s36, v90
	v_fma_f32 v65, v65, s36, v91
	v_fma_f32 v66, v66, s36, v92
	v_fma_f32 v67, v67, s36, v93
	v_fma_f32 v68, v68, s36, v94
	v_fma_f32 v69, v69, s36, v95
	v_fma_f32 v70, v70, s36, v96
	v_fma_f32 v71, v71, s36, v97
	v_fma_f32 v72, v72, s36, v98
	v_fma_f32 v73, v73, s36, v99
	v_fma_f32 v74, v74, s36, v100
	v_fma_f32 v75, v75, s36, v101
	v_fma_f32 v80, v80, s36, v154
	v_fma_f32 v81, v81, s36, v155
	v_fma_f32 v82, v82, s36, v156
	v_fma_f32 v83, v83, s36, v157
	v_max3_f32 v76, v64, v65, v66
	v_max3_f32 v76, v76, v67, v68
	v_max3_f32 v76, v76, v69, v70
	v_max3_f32 v76, v76, v71, v72
	v_max3_f32 v76, v76, v73, v74
	v_max3_f32 v76, v76, v75, v80
	v_max3_f32 v76, v76, v81, v82
	v_max3_f32 v76, v76, v83, s29
	v_mov_b32_e32 v77, v76
	s_nop 1
	v_permlane16_swap_b32_e32 v76, v77
	v_max_f32_e32 v76, v76, v77
	v_mov_b32_e32 v77, v76
	s_nop 1
	v_permlane32_swap_b32_e32 v76, v77
	v_max_f32_e32 v76, v76, v77
	v_cndmask_b32_e64 v76, v148, v76, s[42:43]
	v_max_f32_e32 v77, v161, v76
	v_sub_f32_e32 v248, v160, v187
	v_sub_f32_e32 v0, v161, v77
	v_exp_f32_e32 v236, v248
	v_exp_f32_e32 v0, v0
	v_cndmask_b32_e64 v246, v209, v187, s[44:45]
	v_cndmask_b32_e64 v78, v209, v77, s[42:43]
	v_mov_b32_e32 v160, v187
	v_mov_b32_e32 v161, v77
	v_mul_f32_e32 v36, v36, v236
	v_mul_f32_e32 v37, v37, v236
	v_mul_f32_e32 v32, v32, v0
	v_mul_f32_e32 v33, v33, v0
	v_mul_f32_e32 v34, v34, v236
	v_mul_f32_e32 v35, v35, v236
	v_mul_f32_e32 v30, v30, v0
	v_mul_f32_e32 v31, v31, v0
	v_mul_f32_e32 v48, v48, v236
	v_mul_f32_e32 v49, v49, v236
	v_mul_f32_e32 v28, v28, v0
	v_mul_f32_e32 v29, v29, v0
	v_mul_f32_e32 v46, v46, v236
	v_mul_f32_e32 v47, v47, v236
	v_mul_f32_e32 v26, v26, v0
	v_mul_f32_e32 v27, v27, v0
	v_mul_f32_e32 v44, v44, v236
	v_mul_f32_e32 v45, v45, v236
	v_mul_f32_e32 v24, v24, v0
	v_mul_f32_e32 v25, v25, v0
	v_mul_f32_e32 v42, v42, v236
	v_mul_f32_e32 v43, v43, v236
	v_mul_f32_e32 v22, v22, v0
	v_mul_f32_e32 v23, v23, v0
	v_mul_f32_e32 v52, v52, v236
	v_mul_f32_e32 v53, v53, v236
	v_mul_f32_e32 v20, v20, v0
	v_mul_f32_e32 v21, v21, v0
	v_mul_f32_e32 v50, v50, v236
	v_mul_f32_e32 v51, v51, v236
	v_mul_f32_e32 v18, v18, v0
	v_mul_f32_e32 v19, v19, v0
	v_sub_f32_e32 v170, v170, v246
	v_sub_f32_e32 v171, v171, v246
	v_sub_f32_e32 v64, v64, v78
	v_sub_f32_e32 v65, v65, v78
	v_sub_f32_e32 v172, v172, v246
	v_sub_f32_e32 v173, v173, v246
	v_sub_f32_e32 v66, v66, v78
	v_sub_f32_e32 v67, v67, v78
	v_sub_f32_e32 v174, v174, v246
	v_sub_f32_e32 v175, v175, v246
	v_sub_f32_e32 v68, v68, v78
	v_sub_f32_e32 v69, v69, v78
	v_sub_f32_e32 v176, v176, v246
	v_sub_f32_e32 v177, v177, v246
	v_sub_f32_e32 v70, v70, v78
	v_sub_f32_e32 v71, v71, v78
	v_sub_f32_e32 v178, v178, v246
	v_sub_f32_e32 v179, v179, v246
	v_sub_f32_e32 v72, v72, v78
	v_sub_f32_e32 v73, v73, v78
	v_sub_f32_e32 v180, v180, v246
	v_sub_f32_e32 v181, v181, v246
	v_sub_f32_e32 v74, v74, v78
	v_sub_f32_e32 v75, v75, v78
	v_sub_f32_e32 v182, v182, v246
	v_sub_f32_e32 v183, v183, v246
	v_sub_f32_e32 v80, v80, v78
	v_sub_f32_e32 v81, v81, v78
	v_sub_f32_e32 v184, v184, v246
	v_sub_f32_e32 v185, v185, v246
	v_sub_f32_e32 v82, v82, v78
	v_sub_f32_e32 v83, v83, v78
	v_exp_f32_e32 v170, v170
	v_exp_f32_e32 v64, v64
	v_exp_f32_e32 v171, v171
	v_exp_f32_e32 v65, v65
	v_exp_f32_e32 v172, v172
	v_exp_f32_e32 v66, v66
	v_exp_f32_e32 v173, v173
	v_exp_f32_e32 v67, v67
	v_exp_f32_e32 v174, v174
	v_exp_f32_e32 v68, v68
	v_exp_f32_e32 v175, v175
	v_exp_f32_e32 v69, v69
	v_exp_f32_e32 v176, v176
	v_exp_f32_e32 v70, v70
	v_exp_f32_e32 v177, v177
	v_exp_f32_e32 v71, v71
	v_exp_f32_e32 v178, v178
	v_exp_f32_e32 v72, v72
	v_exp_f32_e32 v179, v179
	v_exp_f32_e32 v73, v73
	v_exp_f32_e32 v180, v180
	v_exp_f32_e32 v74, v74
	v_exp_f32_e32 v181, v181
	v_exp_f32_e32 v75, v75
	v_exp_f32_e32 v182, v182
	v_exp_f32_e32 v80, v80
	v_exp_f32_e32 v183, v183
	v_exp_f32_e32 v81, v81
	v_exp_f32_e32 v184, v184
	v_exp_f32_e32 v82, v82
	v_exp_f32_e32 v185, v185
	v_exp_f32_e32 v83, v83
	s_nop 0
	s_nop 0
	v_add_f32_e32 v238, v170, v172
	v_add_f32_e32 v239, v171, v173
	v_add_f32_e32 v84, v64, v66
	v_add_f32_e32 v85, v65, v67
	v_add_f32_e32 v240, v174, v176
	v_add_f32_e32 v241, v175, v177
	v_add_f32_e32 v86, v68, v70
	v_add_f32_e32 v87, v69, v71
	v_add_f32_e32 v242, v178, v180
	v_add_f32_e32 v243, v179, v181
	v_add_f32_e32 v76, v72, v74
	v_add_f32_e32 v77, v73, v75
	v_add_f32_e32 v244, v182, v184
	v_add_f32_e32 v245, v183, v185
	v_add_f32_e32 v78, v80, v82
	v_add_f32_e32 v79, v81, v83
	v_add_f32_e32 v238, v238, v240
	v_add_f32_e32 v239, v239, v241
	v_add_f32_e32 v84, v84, v86
	v_add_f32_e32 v85, v85, v87
	v_add_f32_e32 v242, v242, v244
	v_add_f32_e32 v243, v243, v245
	v_add_f32_e32 v76, v76, v78
	v_add_f32_e32 v77, v77, v79
	s_nop 0
	s_nop 0
	v_add_f32_e32 v238, v238, v242
	v_add_f32_e32 v239, v239, v243
	v_add_f32_e32 v84, v84, v76
	v_add_f32_e32 v85, v85, v77
	s_nop 0
	s_nop 0
	v_add_f32_e32 v238, v238, v239
	v_add_f32_e32 v84, v84, v85
	v_fma_f32 v144, v144, v236, v238
	v_fma_f32 v145, v145, v0, v84
	v_cvt_pk_bf16_f32 v58, v170, v171
	v_cvt_pk_bf16_f32 v67, v66, v67
	v_cvt_pk_bf16_f32 v59, v172, v173
	v_cvt_pk_bf16_f32 v66, v64, v65
	v_cvt_pk_bf16_f32 v60, v174, v175
	v_cvt_pk_bf16_f32 v68, v68, v69
	v_cvt_pk_bf16_f32 v61, v176, v177
	v_cvt_pk_bf16_f32 v69, v70, v71
	v_cvt_pk_bf16_f32 v54, v178, v179
	v_cvt_pk_bf16_f32 v62, v72, v73
	v_cvt_pk_bf16_f32 v55, v180, v181
	v_cvt_pk_bf16_f32 v63, v74, v75
	v_cvt_pk_bf16_f32 v56, v182, v183
	v_cvt_pk_bf16_f32 v64, v80, v81
	v_cvt_pk_bf16_f32 v57, v184, v185
	v_cvt_pk_bf16_f32 v65, v82, v83
	s_branch .LBB0_446
.Lp1v_only0:
	s_setprio 1
	v_mfma_f32_16x16x32_bf16 v[170:173], v[64:67], v[2:5], 0
	v_mfma_f32_16x16x32_bf16 v[174:177], v[68:71], v[2:5], 0
	v_mfma_f32_16x16x32_bf16 v[170:173], v[54:57], v[6:9], v[170:173]
	v_mfma_f32_16x16x32_bf16 v[178:181], v[72:75], v[2:5], 0
	v_mfma_f32_16x16x32_bf16 v[174:177], v[58:61], v[6:9], v[174:177]
	v_mfma_f32_16x16x32_bf16 v[182:185], v[80:83], v[2:5], 0
	v_mfma_f32_16x16x32_bf16 v[178:181], v[76:79], v[6:9], v[178:181]
	v_mfma_f32_16x16x32_bf16 v[182:185], v[84:87], v[6:9], v[182:185]
	s_setprio 0
	s_nop 7
	s_nop 7
	s_waitcnt lgkmcnt(0)
	v_fma_f32 v170, v170, s36, v90
	v_fma_f32 v171, v171, s36, v91
	v_fma_f32 v172, v172, s36, v92
	v_fma_f32 v173, v173, s36, v93
	v_fma_f32 v174, v174, s36, v94
	v_fma_f32 v175, v175, s36, v95
	v_fma_f32 v176, v176, s36, v96
	v_fma_f32 v177, v177, s36, v97
	v_fma_f32 v178, v178, s36, v98
	v_fma_f32 v179, v179, s36, v99
	v_fma_f32 v180, v180, s36, v100
	v_fma_f32 v181, v181, s36, v101
	v_fma_f32 v182, v182, s36, v154
	v_fma_f32 v183, v183, s36, v155
	v_fma_f32 v184, v184, s36, v156
	v_fma_f32 v185, v185, s36, v157
	v_max3_f32 v186, v170, v171, v172
	v_max3_f32 v186, v186, v173, v174
	v_max3_f32 v186, v186, v175, v176
	v_max3_f32 v186, v186, v177, v178
	v_max3_f32 v186, v186, v179, v180
	v_max3_f32 v186, v186, v181, v182
	v_max3_f32 v186, v186, v183, v184
	v_max3_f32 v186, v186, v185, s29
	v_mov_b32_e32 v187, v186
	s_nop 1
	v_permlane16_swap_b32_e32 v186, v187
	v_max_f32_e32 v186, v186, v187
	v_mov_b32_e32 v187, v186
	s_nop 1
	v_permlane32_swap_b32_e32 v186, v187
	v_max_f32_e32 v186, v186, v187
	v_cndmask_b32_e64 v186, v148, v186, s[44:45]
	v_max_f32_e32 v187, v160, v186
	v_sub_f32_e32 v248, v160, v187
	v_exp_f32_e32 v236, v248
	v_cndmask_b32_e64 v246, v209, v187, s[44:45]
	v_mov_b32_e32 v160, v187
	v_mul_f32_e32 v36, v36, v236
	v_mul_f32_e32 v37, v37, v236
	v_mul_f32_e32 v34, v34, v236
	v_mul_f32_e32 v35, v35, v236
	v_mul_f32_e32 v48, v48, v236
	v_mul_f32_e32 v49, v49, v236
	v_mul_f32_e32 v46, v46, v236
	v_mul_f32_e32 v47, v47, v236
	v_mul_f32_e32 v44, v44, v236
	v_mul_f32_e32 v45, v45, v236
	v_mul_f32_e32 v42, v42, v236
	v_mul_f32_e32 v43, v43, v236
	v_mul_f32_e32 v52, v52, v236
	v_mul_f32_e32 v53, v53, v236
	v_mul_f32_e32 v50, v50, v236
	v_mul_f32_e32 v51, v51, v236
	v_sub_f32_e32 v170, v170, v246
	v_sub_f32_e32 v171, v171, v246
	v_sub_f32_e32 v172, v172, v246
	v_sub_f32_e32 v173, v173, v246
	v_sub_f32_e32 v174, v174, v246
	v_sub_f32_e32 v175, v175, v246
	v_sub_f32_e32 v176, v176, v246
	v_sub_f32_e32 v177, v177, v246
	v_sub_f32_e32 v178, v178, v246
	v_sub_f32_e32 v179, v179, v246
	v_sub_f32_e32 v180, v180, v246
	v_sub_f32_e32 v181, v181, v246
	v_sub_f32_e32 v182, v182, v246
	v_sub_f32_e32 v183, v183, v246
	v_sub_f32_e32 v184, v184, v246
	v_sub_f32_e32 v185, v185, v246
	v_exp_f32_e32 v170, v170
	v_exp_f32_e32 v171, v171
	v_exp_f32_e32 v172, v172
	v_exp_f32_e32 v173, v173
	v_exp_f32_e32 v174, v174
	v_exp_f32_e32 v175, v175
	v_exp_f32_e32 v176, v176
	v_exp_f32_e32 v177, v177
	v_exp_f32_e32 v178, v178
	v_exp_f32_e32 v179, v179
	v_exp_f32_e32 v180, v180
	v_exp_f32_e32 v181, v181
	v_exp_f32_e32 v182, v182
	v_exp_f32_e32 v183, v183
	v_exp_f32_e32 v184, v184
	v_exp_f32_e32 v185, v185
	s_nop 0
	v_add_f32_e32 v238, v170, v172
	v_add_f32_e32 v239, v171, v173
	v_add_f32_e32 v240, v174, v176
	v_add_f32_e32 v241, v175, v177
	v_add_f32_e32 v242, v178, v180
	v_add_f32_e32 v243, v179, v181
	v_add_f32_e32 v244, v182, v184
	v_add_f32_e32 v245, v183, v185
	v_add_f32_e32 v238, v238, v240
	v_add_f32_e32 v239, v239, v241
	v_add_f32_e32 v242, v242, v244
	v_add_f32_e32 v243, v243, v245
	s_nop 0
	v_add_f32_e32 v238, v238, v242
	v_add_f32_e32 v239, v239, v243
	s_nop 0
	v_add_f32_e32 v238, v238, v239
	v_fma_f32 v144, v144, v236, v238
	v_cvt_pk_bf16_f32 v58, v170, v171
	v_cvt_pk_bf16_f32 v59, v172, v173
	v_cvt_pk_bf16_f32 v60, v174, v175
	v_cvt_pk_bf16_f32 v61, v176, v177
	v_cvt_pk_bf16_f32 v54, v178, v179
	v_cvt_pk_bf16_f32 v55, v180, v181
	v_cvt_pk_bf16_f32 v56, v182, v183
	v_cvt_pk_bf16_f32 v57, v184, v185
	s_branch .LBB0_445
.Lp1v_m1:
	s_setprio 1
	v_mfma_f32_16x16x32_bf16 v[64:67], v[64:67], v[10:13], 0
	v_mfma_f32_16x16x32_bf16 v[68:71], v[68:71], v[10:13], 0
	v_mfma_f32_16x16x32_bf16 v[64:67], v[54:57], v[14:17], v[64:67]
	v_mfma_f32_16x16x32_bf16 v[72:75], v[72:75], v[10:13], 0
	v_mfma_f32_16x16x32_bf16 v[68:71], v[58:61], v[14:17], v[68:71]
	v_mfma_f32_16x16x32_bf16 v[80:83], v[80:83], v[10:13], 0
	v_mfma_f32_16x16x32_bf16 v[72:75], v[76:79], v[14:17], v[72:75]
	v_mfma_f32_16x16x32_bf16 v[80:83], v[84:87], v[14:17], v[80:83]
	s_setprio 0
	s_nop 7
	s_nop 7
	v_mov_b32_e32 v54, 0
	v_mov_b32_e32 v55, v54
	v_mov_b32_e32 v56, v54
	v_mov_b32_e32 v57, v54
	v_mov_b32_e32 v58, v54
	v_mov_b32_e32 v59, v54
	v_mov_b32_e32 v60, v54
	v_mov_b32_e32 v61, v54
	s_waitcnt lgkmcnt(0)
	v_fma_f32 v64, v64, s36, v90
	v_fma_f32 v65, v65, s36, v91
	v_fma_f32 v66, v66, s36, v92
	v_fma_f32 v67, v67, s36, v93
	v_fma_f32 v68, v68, s36, v94
	v_fma_f32 v69, v69, s36, v95
	v_fma_f32 v70, v70, s36, v96
	v_fma_f32 v71, v71, s36, v97
	v_fma_f32 v72, v72, s36, v98
	v_fma_f32 v73, v73, s36, v99
	v_fma_f32 v74, v74, s36, v100
	v_fma_f32 v75, v75, s36, v101
	v_fma_f32 v80, v80, s36, v154
	v_fma_f32 v81, v81, s36, v155
	v_fma_f32 v82, v82, s36, v156
	v_fma_f32 v83, v83, s36, v157
	v_max3_f32 v76, v64, v65, v66
	v_max3_f32 v76, v76, v67, v68
	v_max3_f32 v76, v76, v69, v70
	v_max3_f32 v76, v76, v71, v72
	v_max3_f32 v76, v76, v73, v74
	v_max3_f32 v76, v76, v75, v80
	v_max3_f32 v76, v76, v81, v82
	v_max3_f32 v76, v76, v83, s29
	v_mov_b32_e32 v77, v76
	s_nop 1
	v_permlane16_swap_b32_e32 v76, v77
	v_max_f32_e32 v76, v76, v77
	v_mov_b32_e32 v77, v76
	s_nop 1
	v_permlane32_swap_b32_e32 v76, v77
	v_max_f32_e32 v76, v76, v77
	v_cndmask_b32_e64 v76, v148, v76, s[42:43]
	v_max_f32_e32 v77, v161, v76
	v_sub_f32_e32 v0, v161, v77
	v_exp_f32_e32 v0, v0
	v_cndmask_b32_e64 v78, v209, v77, s[42:43]
	v_mov_b32_e32 v161, v77
	v_mul_f32_e32 v32, v32, v0
	v_mul_f32_e32 v33, v33, v0
	v_mul_f32_e32 v30, v30, v0
	v_mul_f32_e32 v31, v31, v0
	v_mul_f32_e32 v28, v28, v0
	v_mul_f32_e32 v29, v29, v0
	v_mul_f32_e32 v26, v26, v0
	v_mul_f32_e32 v27, v27, v0
	v_mul_f32_e32 v24, v24, v0
	v_mul_f32_e32 v25, v25, v0
	v_mul_f32_e32 v22, v22, v0
	v_mul_f32_e32 v23, v23, v0
	v_mul_f32_e32 v20, v20, v0
	v_mul_f32_e32 v21, v21, v0
	v_mul_f32_e32 v18, v18, v0
	v_mul_f32_e32 v19, v19, v0
	v_sub_f32_e32 v64, v64, v78
	v_sub_f32_e32 v65, v65, v78
	v_sub_f32_e32 v66, v66, v78
	v_sub_f32_e32 v67, v67, v78
	v_sub_f32_e32 v68, v68, v78
	v_sub_f32_e32 v69, v69, v78
	v_sub_f32_e32 v70, v70, v78
	v_sub_f32_e32 v71, v71, v78
	v_sub_f32_e32 v72, v72, v78
	v_sub_f32_e32 v73, v73, v78
	v_sub_f32_e32 v74, v74, v78
	v_sub_f32_e32 v75, v75, v78
	v_sub_f32_e32 v80, v80, v78
	v_sub_f32_e32 v81, v81, v78
	v_sub_f32_e32 v82, v82, v78
	v_sub_f32_e32 v83, v83, v78
	v_exp_f32_e32 v64, v64
	v_exp_f32_e32 v65, v65
	v_exp_f32_e32 v66, v66
	v_exp_f32_e32 v67, v67
	v_exp_f32_e32 v68, v68
	v_exp_f32_e32 v69, v69
	v_exp_f32_e32 v70, v70
	v_exp_f32_e32 v71, v71
	v_exp_f32_e32 v72, v72
	v_exp_f32_e32 v73, v73
	v_exp_f32_e32 v74, v74
	v_exp_f32_e32 v75, v75
	v_exp_f32_e32 v80, v80
	v_exp_f32_e32 v81, v81
	v_exp_f32_e32 v82, v82
	v_exp_f32_e32 v83, v83
	s_nop 0
	v_add_f32_e32 v84, v64, v66
	v_add_f32_e32 v85, v65, v67
	v_add_f32_e32 v86, v68, v70
	v_add_f32_e32 v87, v69, v71
	v_add_f32_e32 v76, v72, v74
	v_add_f32_e32 v77, v73, v75
	v_add_f32_e32 v78, v80, v82
	v_add_f32_e32 v79, v81, v83
	v_add_f32_e32 v84, v84, v86
	v_add_f32_e32 v85, v85, v87
	v_add_f32_e32 v76, v76, v78
	v_add_f32_e32 v77, v77, v79
	s_nop 0
	v_add_f32_e32 v84, v84, v76
	v_add_f32_e32 v85, v85, v77
	s_nop 0
	v_add_f32_e32 v84, v84, v85
	v_fma_f32 v145, v145, v0, v84
	v_cvt_pk_bf16_f32 v67, v66, v67
	v_cvt_pk_bf16_f32 v66, v64, v65
	v_cvt_pk_bf16_f32 v68, v68, v69
	v_cvt_pk_bf16_f32 v69, v70, v71
	v_cvt_pk_bf16_f32 v62, v72, v73
	v_cvt_pk_bf16_f32 v63, v74, v75
	v_cvt_pk_bf16_f32 v64, v80, v81
	v_cvt_pk_bf16_f32 v65, v82, v83
	s_branch .LBB0_446

.LBB0_439:
	s_andn2_b64 vcc, exec, s[6:7]
	s_cbranch_vccnz .LBB0_448
	v_and_b32_e32 v0, 1, v164
	v_cmp_eq_u32_e64 s[42:43], 1, v0
	v_and_b32_e32 v0, 1, v162
	v_cmp_eq_u32_e64 s[44:45], 1, v0
	s_or_b64 s[6:7], s[44:45], s[42:43]
	v_cndmask_b32_e64 v54, 0, 1, s[6:7]
	v_cmp_ne_u32_e32 vcc, 0, v54
	s_cbranch_vccz .Lsel_fast
	v_add_u32_e32 v54, s13, v196
	v_add_u32_e32 v62, v54, v194
	v_add_u32_e32 v0, v54, v195
	s_cmp_lg_u64 s[44:45], 0
	ds_read_b128 v[64:67], v62 offset:16384
	ds_read_b128 v[54:57], v0 offset:16384
	ds_read_b128 v[68:71], v62 offset:18432
	ds_read_b128 v[58:61], v0 offset:18432
	ds_read_b128 v[72:75], v62 offset:20480
	ds_read_b128 v[76:79], v0 offset:20480
	ds_read_b128 v[80:83], v62 offset:22528
	ds_read_b128 v[84:87], v0 offset:22528
	ds_read_b32 v188, v193
	s_waitcnt lgkmcnt(0)
	s_cbranch_scc0 .Lp2v_m1
	s_cmp_lg_u64 s[42:43], 0
	s_cbranch_scc0 .Lp2v_only0
	s_setprio 1
	v_mfma_f32_16x16x32_bf16 v[170:173], v[64:67], v[2:5], 0
	v_mfma_f32_16x16x32_bf16 v[174:177], v[68:71], v[2:5], 0
	v_mfma_f32_16x16x32_bf16 v[170:173], v[54:57], v[6:9], v[170:173]
	v_mfma_f32_16x16x32_bf16 v[178:181], v[72:75], v[2:5], 0
	v_mfma_f32_16x16x32_bf16 v[174:177], v[58:61], v[6:9], v[174:177]
	v_mfma_f32_16x16x32_bf16 v[182:185], v[80:83], v[2:5], 0
	v_mfma_f32_16x16x32_bf16 v[178:181], v[76:79], v[6:9], v[178:181]
	v_mfma_f32_16x16x32_bf16 v[182:185], v[84:87], v[6:9], v[182:185]
	v_mfma_f32_16x16x32_bf16 v[64:67], v[64:67], v[10:13], 0
	v_mfma_f32_16x16x32_bf16 v[68:71], v[68:71], v[10:13], 0
	v_mfma_f32_16x16x32_bf16 v[64:67], v[54:57], v[14:17], v[64:67]
	v_mfma_f32_16x16x32_bf16 v[72:75], v[72:75], v[10:13], 0
	v_mfma_f32_16x16x32_bf16 v[68:71], v[58:61], v[14:17], v[68:71]
	v_mfma_f32_16x16x32_bf16 v[80:83], v[80:83], v[10:13], 0
	v_mfma_f32_16x16x32_bf16 v[72:75], v[76:79], v[14:17], v[72:75]
	v_mfma_f32_16x16x32_bf16 v[80:83], v[84:87], v[14:17], v[80:83]
	s_setprio 0
	s_nop 7
	v_max3_f32 v186, v170, v171, v172
	v_max3_f32 v76, v64, v65, v66
	v_max3_f32 v186, v186, v173, v174
	v_max3_f32 v76, v76, v67, v68
	v_max3_f32 v186, v186, v175, v176
	v_max3_f32 v76, v76, v69, v70
	v_max3_f32 v186, v186, v177, v178
	v_max3_f32 v76, v76, v71, v72
	v_max3_f32 v186, v186, v179, v180
	v_max3_f32 v76, v76, v73, v74
	v_max3_f32 v186, v186, v181, v182
	v_max3_f32 v76, v76, v75, v80
	v_max3_f32 v186, v186, v183, v184
	v_max3_f32 v76, v76, v81, v82
	v_max_f32_e32 v186, v186, v185
	v_max_f32_e32 v76, v76, v83
	v_mov_b32_e32 v187, v186
	v_mov_b32_e32 v77, v76
	s_nop 1
	s_nop 1
	v_permlane16_swap_b32_e32 v186, v187
	v_permlane16_swap_b32_e32 v76, v77
	v_max_f32_e32 v186, v186, v187
	v_max_f32_e32 v76, v76, v77
	v_mov_b32_e32 v187, v186
	v_mov_b32_e32 v77, v76
	s_nop 1
	s_nop 1
	v_permlane32_swap_b32_e32 v186, v187
	v_permlane32_swap_b32_e32 v76, v77
	v_max_f32_e32 v186, v186, v187
	v_max_f32_e32 v76, v76, v77
	v_fma_f32 v186, v186, s36, v188
	v_fma_f32 v76, v76, s36, v188
	v_max_f32_e32 v186, s29, v186
	v_max_f32_e32 v76, s29, v76
	v_cndmask_b32_e64 v186, v148, v186, s[44:45]
	v_cndmask_b32_e64 v76, v148, v76, s[42:43]
	v_max_f32_e32 v187, v160, v186
	v_max_f32_e32 v77, v161, v76
	v_sub_f32_e32 v248, v160, v187
	v_sub_f32_e32 v0, v161, v77
	v_exp_f32_e32 v236, v248
	v_exp_f32_e32 v0, v0
	v_cndmask_b32_e64 v186, v209, v187, s[44:45]
	v_cndmask_b32_e64 v76, v209, v77, s[42:43]
	v_mov_b32_e32 v160, v187
	v_mov_b32_e32 v161, v77
	v_sub_f32_e32 v246, v188, v186
	v_sub_f32_e32 v78, v188, v76
	v_mul_f32_e32 v36, v36, v236
	v_mul_f32_e32 v37, v37, v236
	v_mul_f32_e32 v32, v32, v0
	v_mul_f32_e32 v33, v33, v0
	v_mul_f32_e32 v34, v34, v236
	v_mul_f32_e32 v35, v35, v236
	v_mul_f32_e32 v30, v30, v0
	v_mul_f32_e32 v31, v31, v0
	v_mul_f32_e32 v48, v48, v236
	v_mul_f32_e32 v49, v49, v236
	v_mul_f32_e32 v28, v28, v0
	v_mul_f32_e32 v29, v29, v0
	v_mul_f32_e32 v46, v46, v236
	v_mul_f32_e32 v47, v47, v236
	v_mul_f32_e32 v26, v26, v0
	v_mul_f32_e32 v27, v27, v0
	v_mul_f32_e32 v44, v44, v236
	v_mul_f32_e32 v45, v45, v236
	v_mul_f32_e32 v24, v24, v0
	v_mul_f32_e32 v25, v25, v0
	v_mul_f32_e32 v42, v42, v236
	v_mul_f32_e32 v43, v43, v236
	v_mul_f32_e32 v22, v22, v0
	v_mul_f32_e32 v23, v23, v0
	v_mul_f32_e32 v52, v52, v236
	v_mul_f32_e32 v53, v53, v236
	v_mul_f32_e32 v20, v20, v0
	v_mul_f32_e32 v21, v21, v0
	v_mul_f32_e32 v50, v50, v236
	v_mul_f32_e32 v51, v51, v236
	v_mul_f32_e32 v18, v18, v0
	v_mul_f32_e32 v19, v19, v0
	v_fma_f32 v170, v170, s36, v246
	v_fma_f32 v171, v171, s36, v246
	v_fma_f32 v64, v64, s36, v78
	v_fma_f32 v65, v65, s36, v78
	v_fma_f32 v172, v172, s36, v246
	v_fma_f32 v173, v173, s36, v246
	v_fma_f32 v66, v66, s36, v78
	v_fma_f32 v67, v67, s36, v78
	v_fma_f32 v174, v174, s36, v246
	v_fma_f32 v175, v175, s36, v246
	v_fma_f32 v68, v68, s36, v78
	v_fma_f32 v69, v69, s36, v78
	v_fma_f32 v176, v176, s36, v246
	v_fma_f32 v177, v177, s36, v246
	v_fma_f32 v70, v70, s36, v78
	v_fma_f32 v71, v71, s36, v78
	v_fma_f32 v178, v178, s36, v246
	v_fma_f32 v179, v179, s36, v246
	v_fma_f32 v72, v72, s36, v78
	v_fma_f32 v73, v73, s36, v78
	v_fma_f32 v180, v180, s36, v246
	v_fma_f32 v181, v181, s36, v246
	v_fma_f32 v74, v74, s36, v78
	v_fma_f32 v75, v75, s36, v78
	v_fma_f32 v182, v182, s36, v246
	v_fma_f32 v183, v183, s36, v246
	v_fma_f32 v80, v80, s36, v78
	v_fma_f32 v81, v81, s36, v78
	v_fma_f32 v184, v184, s36, v246
	v_fma_f32 v185, v185, s36, v246
	v_fma_f32 v82, v82, s36, v78
	v_fma_f32 v83, v83, s36, v78
	v_exp_f32_e32 v170, v170
	v_exp_f32_e32 v64, v64
	v_exp_f32_e32 v171, v171
	v_exp_f32_e32 v65, v65
	v_exp_f32_e32 v172, v172
	v_exp_f32_e32 v66, v66
	v_exp_f32_e32 v173, v173
	v_exp_f32_e32 v67, v67
	v_exp_f32_e32 v174, v174
	v_exp_f32_e32 v68, v68
	v_exp_f32_e32 v175, v175
	v_exp_f32_e32 v69, v69
	v_exp_f32_e32 v176, v176
	v_exp_f32_e32 v70, v70
	v_exp_f32_e32 v177, v177
	v_exp_f32_e32 v71, v71
	v_exp_f32_e32 v178, v178
	v_exp_f32_e32 v72, v72
	v_exp_f32_e32 v179, v179
	v_exp_f32_e32 v73, v73
	v_exp_f32_e32 v180, v180
	v_exp_f32_e32 v74, v74
	v_exp_f32_e32 v181, v181
	v_exp_f32_e32 v75, v75
	v_exp_f32_e32 v182, v182
	v_exp_f32_e32 v80, v80
	v_exp_f32_e32 v183, v183
	v_exp_f32_e32 v81, v81
	v_exp_f32_e32 v184, v184
	v_exp_f32_e32 v82, v82
	v_exp_f32_e32 v185, v185
	v_exp_f32_e32 v83, v83
	s_nop 0
	s_nop 0
	v_add_f32_e32 v238, v170, v172
	v_add_f32_e32 v239, v171, v173
	v_add_f32_e32 v84, v64, v66
	v_add_f32_e32 v85, v65, v67
	v_add_f32_e32 v240, v174, v176
	v_add_f32_e32 v241, v175, v177
	v_add_f32_e32 v86, v68, v70
	v_add_f32_e32 v87, v69, v71
	v_add_f32_e32 v242, v178, v180
	v_add_f32_e32 v243, v179, v181
	v_add_f32_e32 v76, v72, v74
	v_add_f32_e32 v77, v73, v75
	v_add_f32_e32 v244, v182, v184
	v_add_f32_e32 v245, v183, v185
	v_add_f32_e32 v78, v80, v82
	v_add_f32_e32 v79, v81, v83
	v_add_f32_e32 v238, v238, v240
	v_add_f32_e32 v239, v239, v241
	v_add_f32_e32 v84, v84, v86
	v_add_f32_e32 v85, v85, v87
	v_add_f32_e32 v242, v242, v244
	v_add_f32_e32 v243, v243, v245
	v_add_f32_e32 v76, v76, v78
	v_add_f32_e32 v77, v77, v79
	s_nop 0
	s_nop 0
	v_add_f32_e32 v238, v238, v242
	v_add_f32_e32 v239, v239, v243
	v_add_f32_e32 v84, v84, v76
	v_add_f32_e32 v85, v85, v77
	s_nop 0
	s_nop 0
	v_add_f32_e32 v238, v238, v239
	v_add_f32_e32 v84, v84, v85
	v_fma_f32 v144, v144, v236, v238
	v_fma_f32 v145, v145, v0, v84
	v_cvt_pk_bf16_f32 v58, v170, v171
	v_cvt_pk_bf16_f32 v67, v66, v67
	v_cvt_pk_bf16_f32 v59, v172, v173
	v_cvt_pk_bf16_f32 v66, v64, v65
	v_cvt_pk_bf16_f32 v60, v174, v175
	v_cvt_pk_bf16_f32 v68, v68, v69
	v_cvt_pk_bf16_f32 v61, v176, v177
	v_cvt_pk_bf16_f32 v69, v70, v71
	v_cvt_pk_bf16_f32 v54, v178, v179
	v_cvt_pk_bf16_f32 v62, v72, v73
	v_cvt_pk_bf16_f32 v55, v180, v181
	v_cvt_pk_bf16_f32 v63, v74, v75
	v_cvt_pk_bf16_f32 v56, v182, v183
	v_cvt_pk_bf16_f32 v64, v80, v81
	v_cvt_pk_bf16_f32 v57, v184, v185
	v_cvt_pk_bf16_f32 v65, v82, v83
	s_branch .LBB0_446
.Lp2v_only0:
	s_setprio 1
	v_mfma_f32_16x16x32_bf16 v[170:173], v[64:67], v[2:5], 0
	v_mfma_f32_16x16x32_bf16 v[174:177], v[68:71], v[2:5], 0
	v_mfma_f32_16x16x32_bf16 v[170:173], v[54:57], v[6:9], v[170:173]
	v_mfma_f32_16x16x32_bf16 v[178:181], v[72:75], v[2:5], 0
	v_mfma_f32_16x16x32_bf16 v[174:177], v[58:61], v[6:9], v[174:177]
	v_mfma_f32_16x16x32_bf16 v[182:185], v[80:83], v[2:5], 0
	v_mfma_f32_16x16x32_bf16 v[178:181], v[76:79], v[6:9], v[178:181]
	v_mfma_f32_16x16x32_bf16 v[182:185], v[84:87], v[6:9], v[182:185]
	s_setprio 0
	s_nop 7
	s_nop 7
	v_max3_f32 v186, v170, v171, v172
	v_max3_f32 v186, v186, v173, v174
	v_max3_f32 v186, v186, v175, v176
	v_max3_f32 v186, v186, v177, v178
	v_max3_f32 v186, v186, v179, v180
	v_max3_f32 v186, v186, v181, v182
	v_max3_f32 v186, v186, v183, v184
	v_max_f32_e32 v186, v186, v185
	v_mov_b32_e32 v187, v186
	s_nop 1
	v_permlane16_swap_b32_e32 v186, v187
	v_max_f32_e32 v186, v186, v187
	v_mov_b32_e32 v187, v186
	s_nop 1
	v_permlane32_swap_b32_e32 v186, v187
	v_max_f32_e32 v186, v186, v187
	v_fma_f32 v186, v186, s36, v188
	v_max_f32_e32 v186, s29, v186
	v_cndmask_b32_e64 v186, v148, v186, s[44:45]
	v_max_f32_e32 v187, v160, v186
	v_sub_f32_e32 v248, v160, v187
	v_exp_f32_e32 v236, v248
	v_cndmask_b32_e64 v186, v209, v187, s[44:45]
	v_mov_b32_e32 v160, v187
	v_sub_f32_e32 v246, v188, v186
	v_mul_f32_e32 v36, v36, v236
	v_mul_f32_e32 v37, v37, v236
	v_mul_f32_e32 v34, v34, v236
	v_mul_f32_e32 v35, v35, v236
	v_mul_f32_e32 v48, v48, v236
	v_mul_f32_e32 v49, v49, v236
	v_mul_f32_e32 v46, v46, v236
	v_mul_f32_e32 v47, v47, v236
	v_mul_f32_e32 v44, v44, v236
	v_mul_f32_e32 v45, v45, v236
	v_mul_f32_e32 v42, v42, v236
	v_mul_f32_e32 v43, v43, v236
	v_mul_f32_e32 v52, v52, v236
	v_mul_f32_e32 v53, v53, v236
	v_mul_f32_e32 v50, v50, v236
	v_mul_f32_e32 v51, v51, v236
	v_fma_f32 v170, v170, s36, v246
	v_fma_f32 v171, v171, s36, v246
	v_fma_f32 v172, v172, s36, v246
	v_fma_f32 v173, v173, s36, v246
	v_fma_f32 v174, v174, s36, v246
	v_fma_f32 v175, v175, s36, v246
	v_fma_f32 v176, v176, s36, v246
	v_fma_f32 v177, v177, s36, v246
	v_fma_f32 v178, v178, s36, v246
	v_fma_f32 v179, v179, s36, v246
	v_fma_f32 v180, v180, s36, v246
	v_fma_f32 v181, v181, s36, v246
	v_fma_f32 v182, v182, s36, v246
	v_fma_f32 v183, v183, s36, v246
	v_fma_f32 v184, v184, s36, v246
	v_fma_f32 v185, v185, s36, v246
	v_exp_f32_e32 v170, v170
	v_exp_f32_e32 v171, v171
	v_exp_f32_e32 v172, v172
	v_exp_f32_e32 v173, v173
	v_exp_f32_e32 v174, v174
	v_exp_f32_e32 v175, v175
	v_exp_f32_e32 v176, v176
	v_exp_f32_e32 v177, v177
	v_exp_f32_e32 v178, v178
	v_exp_f32_e32 v179, v179
	v_exp_f32_e32 v180, v180
	v_exp_f32_e32 v181, v181
	v_exp_f32_e32 v182, v182
	v_exp_f32_e32 v183, v183
	v_exp_f32_e32 v184, v184
	v_exp_f32_e32 v185, v185
	s_nop 0
	v_add_f32_e32 v238, v170, v172
	v_add_f32_e32 v239, v171, v173
	v_add_f32_e32 v240, v174, v176
	v_add_f32_e32 v241, v175, v177
	v_add_f32_e32 v242, v178, v180
	v_add_f32_e32 v243, v179, v181
	v_add_f32_e32 v244, v182, v184
	v_add_f32_e32 v245, v183, v185
	v_add_f32_e32 v238, v238, v240
	v_add_f32_e32 v239, v239, v241
	v_add_f32_e32 v242, v242, v244
	v_add_f32_e32 v243, v243, v245
	s_nop 0
	v_add_f32_e32 v238, v238, v242
	v_add_f32_e32 v239, v239, v243
	s_nop 0
	v_add_f32_e32 v238, v238, v239
	v_fma_f32 v144, v144, v236, v238
	v_cvt_pk_bf16_f32 v58, v170, v171
	v_cvt_pk_bf16_f32 v59, v172, v173
	v_cvt_pk_bf16_f32 v60, v174, v175
	v_cvt_pk_bf16_f32 v61, v176, v177
	v_cvt_pk_bf16_f32 v54, v178, v179
	v_cvt_pk_bf16_f32 v55, v180, v181
	v_cvt_pk_bf16_f32 v56, v182, v183
	v_cvt_pk_bf16_f32 v57, v184, v185
	s_branch .LBB0_445
.Lp2v_m1:
	s_setprio 1
	v_mfma_f32_16x16x32_bf16 v[64:67], v[64:67], v[10:13], 0
	v_mfma_f32_16x16x32_bf16 v[68:71], v[68:71], v[10:13], 0
	v_mfma_f32_16x16x32_bf16 v[64:67], v[54:57], v[14:17], v[64:67]
	v_mfma_f32_16x16x32_bf16 v[72:75], v[72:75], v[10:13], 0
	v_mfma_f32_16x16x32_bf16 v[68:71], v[58:61], v[14:17], v[68:71]
	v_mfma_f32_16x16x32_bf16 v[80:83], v[80:83], v[10:13], 0
	v_mfma_f32_16x16x32_bf16 v[72:75], v[76:79], v[14:17], v[72:75]
	v_mfma_f32_16x16x32_bf16 v[80:83], v[84:87], v[14:17], v[80:83]
	s_setprio 0
	s_nop 7
	s_nop 7
	v_mov_b32_e32 v54, 0
	v_mov_b32_e32 v55, v54
	v_mov_b32_e32 v56, v54
	v_mov_b32_e32 v57, v54
	v_mov_b32_e32 v58, v54
	v_mov_b32_e32 v59, v54
	v_mov_b32_e32 v60, v54
	v_mov_b32_e32 v61, v54
	v_max3_f32 v76, v64, v65, v66
	v_max3_f32 v76, v76, v67, v68
	v_max3_f32 v76, v76, v69, v70
	v_max3_f32 v76, v76, v71, v72
	v_max3_f32 v76, v76, v73, v74
	v_max3_f32 v76, v76, v75, v80
	v_max3_f32 v76, v76, v81, v82
	v_max_f32_e32 v76, v76, v83
	v_mov_b32_e32 v77, v76
	s_nop 1
	v_permlane16_swap_b32_e32 v76, v77
	v_max_f32_e32 v76, v76, v77
	v_mov_b32_e32 v77, v76
	s_nop 1
	v_permlane32_swap_b32_e32 v76, v77
	v_max_f32_e32 v76, v76, v77
	v_fma_f32 v76, v76, s36, v188
	v_max_f32_e32 v76, s29, v76
	v_cndmask_b32_e64 v76, v148, v76, s[42:43]
	v_max_f32_e32 v77, v161, v76
	v_sub_f32_e32 v0, v161, v77
	v_exp_f32_e32 v0, v0
	v_cndmask_b32_e64 v76, v209, v77, s[42:43]
	v_mov_b32_e32 v161, v77
	v_sub_f32_e32 v78, v188, v76
	v_mul_f32_e32 v32, v32, v0
	v_mul_f32_e32 v33, v33, v0
	v_mul_f32_e32 v30, v30, v0
	v_mul_f32_e32 v31, v31, v0
	v_mul_f32_e32 v28, v28, v0
	v_mul_f32_e32 v29, v29, v0
	v_mul_f32_e32 v26, v26, v0
	v_mul_f32_e32 v27, v27, v0
	v_mul_f32_e32 v24, v24, v0
	v_mul_f32_e32 v25, v25, v0
	v_mul_f32_e32 v22, v22, v0
	v_mul_f32_e32 v23, v23, v0
	v_mul_f32_e32 v20, v20, v0
	v_mul_f32_e32 v21, v21, v0
	v_mul_f32_e32 v18, v18, v0
	v_mul_f32_e32 v19, v19, v0
	v_fma_f32 v64, v64, s36, v78
	v_fma_f32 v65, v65, s36, v78
	v_fma_f32 v66, v66, s36, v78
	v_fma_f32 v67, v67, s36, v78
	v_fma_f32 v68, v68, s36, v78
	v_fma_f32 v69, v69, s36, v78
	v_fma_f32 v70, v70, s36, v78
	v_fma_f32 v71, v71, s36, v78
	v_fma_f32 v72, v72, s36, v78
	v_fma_f32 v73, v73, s36, v78
	v_fma_f32 v74, v74, s36, v78
	v_fma_f32 v75, v75, s36, v78
	v_fma_f32 v80, v80, s36, v78
	v_fma_f32 v81, v81, s36, v78
	v_fma_f32 v82, v82, s36, v78
	v_fma_f32 v83, v83, s36, v78
	v_exp_f32_e32 v64, v64
	v_exp_f32_e32 v65, v65
	v_exp_f32_e32 v66, v66
	v_exp_f32_e32 v67, v67
	v_exp_f32_e32 v68, v68
	v_exp_f32_e32 v69, v69
	v_exp_f32_e32 v70, v70
	v_exp_f32_e32 v71, v71
	v_exp_f32_e32 v72, v72
	v_exp_f32_e32 v73, v73
	v_exp_f32_e32 v74, v74
	v_exp_f32_e32 v75, v75
	v_exp_f32_e32 v80, v80
	v_exp_f32_e32 v81, v81
	v_exp_f32_e32 v82, v82
	v_exp_f32_e32 v83, v83
	s_nop 0
	v_add_f32_e32 v84, v64, v66
	v_add_f32_e32 v85, v65, v67
	v_add_f32_e32 v86, v68, v70
	v_add_f32_e32 v87, v69, v71
	v_add_f32_e32 v76, v72, v74
	v_add_f32_e32 v77, v73, v75
	v_add_f32_e32 v78, v80, v82
	v_add_f32_e32 v79, v81, v83
	v_add_f32_e32 v84, v84, v86
	v_add_f32_e32 v85, v85, v87
	v_add_f32_e32 v76, v76, v78
	v_add_f32_e32 v77, v77, v79
	s_nop 0
	v_add_f32_e32 v84, v84, v76
	v_add_f32_e32 v85, v85, v77
	s_nop 0
	v_add_f32_e32 v84, v84, v85
	v_fma_f32 v145, v145, v0, v84
	v_cvt_pk_bf16_f32 v67, v66, v67
	v_cvt_pk_bf16_f32 v66, v64, v65
	v_cvt_pk_bf16_f32 v68, v68, v69
	v_cvt_pk_bf16_f32 v69, v70, v71
	v_cvt_pk_bf16_f32 v62, v72, v73
	v_cvt_pk_bf16_f32 v63, v74, v75
	v_cvt_pk_bf16_f32 v64, v80, v81
	v_cvt_pk_bf16_f32 v65, v82, v83
	s_branch .LBB0_446
